# v63 + MoBA step loop: per-block gathered-query counts read from a per-unit VGPR snapshot with v_readlane instead of an LDS read + readfirstlane per tile
# speedup vs baseline: 1.0017x; 1.0017x over previous
; template <bool MOBA>
; __device__ __forceinline__ void attn_unit(unsigned char* lds, LAS unsigned char* lds3, const Params& p, int b, int h, int qb) {
;     ...
;     for (int st = 0; st < NT / 2; ++st) {
;         const int buf = st & 1;
;         if (st + 1 < NT / 2) {
; #pragma unroll
;             for (int sb = 0; sb < 2; ++sb) { const size_t o_ = (size_t)(NT - 1 - (2 * st + 2 + sb)) * 64 * DM; kreg[sb] = *(const u32x4*)(kp + o_); vreg[sb] = *(const u32x4*)(vp + o_); } }
;       for (int sub = 0; sub < 2; ++sub) {
;         const int it = 2 * st + sub, t = NT - 1 - it, slot = buf * 2 + sub;
;         const int tl = t - 4 * qb;
;         if (!MOBA && !wdone && (fq0 - Fs[64 * t + 63]) < -141.f) wdone = true;
;         bool active = (tl <= (w >> 1)) && !wdone;
;         if (MOBA && it == 0) ATT_QPREF(qb - 1);
.LBB0_426:
	s_or_b32 s4, s34, 1
	s_mov_b32 s5, s75
	s_lshl_b64 s[4:5], s[4:5], 17
	s_mov_b32 s35, s75
	v_lshl_add_u64 v[20:21], v[36:37], 0, s[4:5]
	s_waitcnt lgkmcnt(4)
	v_lshl_add_u64 v[24:25], v[38:39], 0, s[4:5]
	s_lshl_b64 s[4:5], s[34:35], 17
	s_waitcnt lgkmcnt(0)
	v_lshl_add_u64 v[28:29], v[36:37], 0, s[4:5]
	v_lshl_add_u64 v[32:33], v[38:39], 0, s[4:5]
	s_barrier
	v_mbcnt_lo_u32_b32 v234, -1, 0
	v_mbcnt_hi_u32_b32 v234, -1, v234
	v_lshlrev_b32_e32 v234, 2, v234
	v_add_u32_e32 v234, 0x14d00, v234
	ds_read_b32 v232, v234
	s_waitcnt lgkmcnt(0)
	global_load_dwordx4 v[20:23], v[20:21], off offset:1024
	s_nop 0
	global_load_dwordx4 v[24:27], v[24:25], off offset:1024
	s_nop 0
	global_load_dwordx4 v[28:31], v[28:29], off offset:1024
	s_nop 0
	global_load_dwordx4 v[32:35], v[32:33], off offset:1024
	s_add_i32 s20, s86, -1
	s_lshl_b32 s4, s20, 8
	s_add_i32 s4, s4, 0
	v_mov_b64_e32 v[50:51], v[14:15]
	v_mov_b64_e32 v[46:47], v[18:19]
	v_mov_b64_e32 v[42:43], v[6:7]
	v_mov_b64_e32 v[38:39], v[10:11]
	v_or_b32_e32 v121, 16, v120
	s_add_i32 s4, s4, 0x13880
	s_and_b64 vcc, exec, s[10:11]
	v_mov_b64_e32 v[48:49], v[12:13]
	v_mov_b64_e32 v[44:45], v[16:17]
	v_mov_b64_e32 v[40:41], v[4:5]
	v_mov_b64_e32 v[36:37], v[8:9]
	s_cbranch_vccnz .LBB0_433
	s_lshl_b32 s5, s20, 2
	s_add_i32 s5, s5, 0
	s_add_i32 s5, s5, 0x14d00
	v_mov_b64_e32 v[38:39], v[10:11]
	v_mov_b64_e32 v[42:43], v[6:7]
	v_mov_b64_e32 v[46:47], v[18:19]
	v_mov_b64_e32 v[50:51], v[14:15]
	s_waitcnt lgkmcnt(0)
	s_sub_i32 s5, s5, 0x14d00
	s_lshr_b32 s5, s5, 2
	s_nop 3
	v_readlane_b32 s5, v232, s5
	v_mov_b64_e32 v[36:37], v[8:9]
	v_mov_b64_e32 v[40:41], v[4:5]
	s_cmp_ge_i32 s41, s5
	v_mov_b64_e32 v[44:45], v[16:17]
	v_mov_b64_e32 v[48:49], v[12:13]
	s_cbranch_scc1 .LBB0_433
	v_cmp_gt_i32_e32 vcc, s5, v120
	v_mov_b64_e32 v[44:45], 0
	v_mov_b64_e32 v[36:37], 0
	s_and_saveexec_b64 s[6:7], vcc
	s_cbranch_execz .LBB0_430
	v_add_u32_e32 v3, s4, v120
	ds_read_u8 v3, v3
	v_mov_b32_e32 v37, s75
	s_waitcnt lgkmcnt(0)
	v_and_b32_e32 v36, 0xffff, v3

; template <bool MOBA>
; __device__ __forceinline__ void attn_unit(unsigned char* lds, LAS unsigned char* lds3, const Params& p, int b, int h, int qb) {
;     ...
;         if (MOBA && tl < 0) {
;             const int j = t >> 2; const int nj = __builtin_amdgcn_readfirstlane(njs[j]);
;             active = (32 * w < nj);
;             if (active && (t & 3) == 3) {
; #pragma unroll
;                 for (int jb = 0; jb < 2; ++jb) { const int slot = 32 * w + 16 * jb + fr; qv[jb] = slot < nj; const int q = qv[jb] ? (int)listq[j * 256 + slot] : 0; qpl[jb] = q; mrc[jb] = mrefs[q];
; #pragma unroll
;                     for (int ks = 0; ks < 2; ++ks) qf[jb][ks] = qn[jb][ks]; }
;             }
.LBB0_442:
	s_add_i32 s5, s34, 0
	s_add_i32 s5, s5, 0x14d00
	s_mov_b64 s[12:13], -1
	s_mov_b64 s[10:11], -1
	v_mov_b64_e32 v[124:125], v[120:121]
	s_waitcnt lgkmcnt(0)
	s_sub_i32 s14, s5, 0x14d00
	s_lshr_b32 s14, s14, 2
	s_nop 3
	v_readlane_b32 s14, v232, s14
	s_cmp_lt_i32 s41, s14
	s_cselect_b64 s[6:7], -1, 0
	s_cmp_ge_i32 s41, s14
	s_cbranch_scc1 .LBB0_448
	s_add_i32 s10, s42, 0
	s_add_i32 s12, s10, 0x13880
	v_cmp_gt_i32_e64 s[10:11], s14, v120
	v_mov_b32_e32 v125, 0
	v_add_u32_e32 v3, s12, v120
	v_mov_b32_e32 v124, 0
	s_and_saveexec_b64 s[12:13], s[10:11]
	ds_read_u8 v124, v3
	s_or_b64 exec, exec, s[12:13]
	s_waitcnt lgkmcnt(0)
	v_lshl_add_u32 v4, v124, 2, 0
	v_add_u32_e32 v4, 0x14880, v4
	ds_read_b32 v122, v4
	v_cmp_gt_i32_e64 s[12:13], s14, v121
	s_and_saveexec_b64 s[14:15], s[12:13]
	ds_read_u8 v125, v3 offset:16
	s_or_b64 exec, exec, s[14:15]
	s_waitcnt lgkmcnt(0)
	v_lshl_add_u32 v3, v125, 2, 0
	v_add_u32_e32 v3, 0x14880, v3
	ds_read_b32 v123, v3
	s_waitcnt vmcnt(0)
	v_mov_b64_e32 v[12:13], v[48:49]
	v_mov_b64_e32 v[16:17], v[44:45]
	v_mov_b64_e32 v[4:5], v[40:41]
	v_mov_b64_e32 v[8:9], v[36:37]
	v_mov_b64_e32 v[14:15], v[50:51]
	v_mov_b64_e32 v[18:19], v[46:47]
	v_mov_b64_e32 v[6:7], v[42:43]
	v_mov_b64_e32 v[10:11], v[38:39]

; template <bool MOBA>
; __device__ __forceinline__ void attn_unit(unsigned char* lds, LAS unsigned char* lds3, const Params& p, int b, int h, int qb) {
;     ...
;         if (MOBA && tl < 0) {
;             const int j = t >> 2; const int nj = __builtin_amdgcn_readfirstlane(njs[j]);
;             active = (32 * w < nj);
;             if (active && (t & 3) == 3) {
.LBB0_455:
	s_add_i32 s5, s34, 0
	s_add_i32 s5, s5, 0x14d00
	s_waitcnt lgkmcnt(0)
	s_sub_i32 s5, s5, 0x14d00
	s_lshr_b32 s5, s5, 2
	s_nop 3
	v_readlane_b32 s5, v232, s5
	s_cmp_lt_i32 s41, s5
	s_cselect_b64 s[6:7], -1, 0
	s_andn2_b64 vcc, exec, s[6:7]
	s_cbranch_vccnz .LBB0_459

; template <bool MOBA>
; __device__ __forceinline__ void attn_unit(unsigned char* lds, LAS unsigned char* lds3, const Params& p, int b, int h, int qb) {
;     ...
;         if (MOBA && tl < 0) {
;             const int j = t >> 2; const int nj = __builtin_amdgcn_readfirstlane(njs[j]);
;             active = (32 * w < nj);
;             if (active && (t & 3) == 3) {
; #pragma unroll
;                 for (int jb = 0; jb < 2; ++jb) { const int slot = 32 * w + 16 * jb + fr; qv[jb] = slot < nj; const int q = qv[jb] ? (int)listq[j * 256 + slot] : 0; qpl[jb] = q; mrc[jb] = mrefs[q];
; #pragma unroll
;                     for (int ks = 0; ks < 2; ++ks) qf[jb][ks] = qn[jb][ks]; }
;             }
;             if ((t & 3) == 3) ATT_QPREF(j - 1);
.LBB0_463:
	s_add_i32 s28, s34, s27
	s_add_i32 s4, s28, 1
	s_add_i32 s5, s27, 1
	s_cmp_le_i32 s5, s21
	s_cselect_b64 s[6:7], -1, 0
	s_cmp_gt_i32 s5, -1
	s_cbranch_scc1 .LBB0_478
	s_and_b32 s5, s4, -4
	s_add_i32 s29, s5, 0
	s_add_i32 s29, s29, 0x14d00
	s_ashr_i32 s5, s4, 2
	s_waitcnt lgkmcnt(0)
	s_sub_i32 s18, s29, 0x14d00
	s_lshr_b32 s18, s18, 2
	s_nop 3
	v_readlane_b32 s18, v232, s18
	s_cmp_lt_i32 s41, s18
	s_cselect_b64 s[6:7], -1, 0
	s_and_b32 s16, s4, 3
	s_cmp_eq_u32 s16, 3
	s_cselect_b64 s[16:17], -1, 0
	s_and_b64 s[30:31], s[16:17], s[6:7]
	s_andn2_b64 vcc, exec, s[30:31]
	s_cbranch_vccnz .LBB0_470
	s_lshl_b32 s10, s5, 8
	s_add_i32 s10, s10, 0
	s_add_i32 s12, s10, 0x13880
	v_cmp_gt_i32_e64 s[10:11], s18, v120
	v_mov_b32_e32 v125, 0
	v_add_u32_e32 v1, s12, v120
	v_mov_b32_e32 v124, 0
	s_and_saveexec_b64 s[12:13], s[10:11]
	ds_read_u8 v124, v1
	s_or_b64 exec, exec, s[12:13]
	s_waitcnt lgkmcnt(0)
	v_lshl_add_u32 v2, v124, 2, 0
	v_add_u32_e32 v2, 0x14880, v2
	ds_read_b32 v122, v2
	v_cmp_gt_i32_e64 s[12:13], s18, v121
	s_and_saveexec_b64 s[18:19], s[12:13]
	ds_read_u8 v125, v1 offset:16
	s_or_b64 exec, exec, s[18:19]
	s_waitcnt lgkmcnt(0)
	v_lshl_add_u32 v1, v125, 2, 0
	v_add_u32_e32 v1, 0x14880, v1
	ds_read_b32 v123, v1
	s_waitcnt vmcnt(4)
	v_mov_b64_e32 v[12:13], v[48:49]
	v_mov_b64_e32 v[16:17], v[44:45]
	v_mov_b64_e32 v[4:5], v[40:41]
	v_mov_b64_e32 v[8:9], v[36:37]
	v_mov_b64_e32 v[14:15], v[50:51]
	v_mov_b64_e32 v[18:19], v[46:47]
	v_mov_b64_e32 v[6:7], v[42:43]
	v_mov_b64_e32 v[10:11], v[38:39]
.LBB0_470:
	s_andn2_b64 vcc, exec, s[16:17]
	s_cbranch_vccnz .LBB0_478
	s_cmp_lt_i32 s5, 1
	s_cbranch_scc1 .LBB0_478
	s_add_i32 s16, s29, -4
	s_waitcnt lgkmcnt(0)
	s_sub_i32 s18, s16, 0x14d00
	s_lshr_b32 s18, s18, 2
	s_nop 3
	v_readlane_b32 s18, v232, s18
	s_cmp_ge_i32 s41, s18
	s_cbranch_scc1 .LBB0_478
	s_lshl_b32 s5, s5, 8
	s_add_i32 s5, s5, 0
	s_add_i32 s5, s5, 0x13780
	v_cmp_gt_i32_e32 vcc, s18, v120
	v_mov_b64_e32 v[2:3], 0
	v_add_u32_e32 v1, s5, v120
	s_waitcnt vmcnt(3)
	v_mov_b64_e32 v[36:37], 0
	s_and_saveexec_b64 s[16:17], vcc
	s_cbranch_execz .LBB0_475
	ds_read_u8 v36, v1
	v_mov_b32_e32 v37, s75
	s_waitcnt lgkmcnt(0)
	v_and_b32_e32 v36, 0xffff, v36

; template <bool MOBA>
; __device__ __forceinline__ void attn_unit(unsigned char* lds, LAS unsigned char* lds3, const Params& p, int b, int h, int qb) {
;     ...
;         if (MOBA && tl < 0) {
;             const int j = t >> 2; const int nj = __builtin_amdgcn_readfirstlane(njs[j]);
;             active = (32 * w < nj);
;             if (active && (t & 3) == 3) {
.LBB0_484:
	s_and_b32 s4, s28, -4
	s_add_i32 s4, s4, 0
	s_add_i32 s4, s4, 0x14d00
	s_waitcnt lgkmcnt(0)
	s_sub_i32 s4, s4, 0x14d00
	s_lshr_b32 s4, s4, 2
	s_nop 3
	v_readlane_b32 s4, v232, s4
	s_cmp_lt_i32 s41, s4
	s_cselect_b64 s[16:17], -1, 0
	s_andn2_b64 vcc, exec, s[16:17]
	s_cbranch_vccnz .LBB0_492
	s_branch .LBB0_487
